# scan post-barrier LDS reads batched on top of v30
# speedup vs baseline: 1.0245x; 1.0051x over previous
.LBB0_708:
	ds_read2st64_b32 v[174:175], v137 offset1:1
	ds_read2st64_b32 v[176:177], v137 offset0:2 offset1:3
	ds_read2st64_b32 v[178:179], v137 offset0:4 offset1:5
	ds_read2st64_b32 v[180:181], v137 offset0:6 offset1:7
	ds_read_b128 v[84:87], v163
	ds_read_b128 v[80:83], v163 offset:16
	s_waitcnt vmcnt(1)
	v_lshlrev_b32_e32 v92, 16, v76
	v_and_b32_e32 v93, 0xffff0000, v76
	v_mul_f32_e32 v76, 0xbfb8aa3b, v92
	v_exp_f32_e32 v76, v76
	s_waitcnt lgkmcnt(5)
	v_add_f32_e32 v182, 0, v174
	v_add_f32_e32 v183, v182, v175
	v_add_f32_e32 v76, 1.0, v76
	v_rcp_f32_e32 v94, v76
	v_mul_f32_e32 v76, 0xbfb8aa3b, v93
	v_exp_f32_e32 v76, v76
	s_waitcnt lgkmcnt(4)
	v_add_f32_e32 v182, v183, v176
	v_add_f32_e32 v183, v182, v177
	v_add_f32_e32 v76, 1.0, v76
	v_rcp_f32_e32 v95, v76
	s_mov_b32 s8, 0xd000000
	s_add_u32 s17, s17, 4
	s_waitcnt lgkmcnt(3)
	v_add_f32_e32 v182, v183, v178
	v_add_f32_e32 v183, v182, v179
	v_pk_mul_f32 v[92:93], v[94:95], v[92:93]
	s_addc_u32 s18, s18, 0
	s_add_i32 s0, s0, -1
	v_lshl_add_u64 v[122:123], v[122:123], 0, s[6:7]
	s_waitcnt lgkmcnt(2)
	v_add_f32_e32 v182, v183, v180
	v_add_f32_e32 v182, v182, v181
	v_fmamk_f32 v182, v182, 0x3c000000, v162
	v_rsq_f32_e32 v88, v182
	v_lshl_add_u64 v[126:127], v[126:127], 0, s[6:7]
	s_cmp_lg_u32 s0, 0
	s_waitcnt lgkmcnt(1)
	v_and_b32_e32 v91, 0xffff0000, v84
	v_lshlrev_b32_e32 v90, 16, v84
	v_pk_mul_f32 v[90:91], v[88:89], v[90:91] op_sel_hi:[0,1]
	v_pk_mul_f32 v[90:91], v[92:93], v[90:91]
	v_and_b32_e32 v93, 0xffff0000, v85
	v_lshlrev_b32_e32 v92, 16, v85
	v_and_b32_e32 v85, 0xffff0000, v77
	v_lshlrev_b32_e32 v84, 16, v77
	v_mul_f32_e32 v76, 0xbfb8aa3b, v84
	v_mul_f32_e32 v77, 0xbfb8aa3b, v85
	v_exp_f32_e32 v76, v76
	v_exp_f32_e32 v77, v77
	v_pk_mul_f32 v[92:93], v[88:89], v[92:93] op_sel_hi:[0,1]
	v_add_f32_e32 v76, 1.0, v76
	v_add_f32_e32 v77, 1.0, v77
	v_rcp_f32_e32 v76, v76
	v_rcp_f32_e32 v77, v77
	s_nop 0
	v_pk_mul_f32 v[76:77], v[76:77], v[84:85]
	s_nop 0
	v_pk_mul_f32 v[84:85], v[76:77], v[92:93]
	v_lshlrev_b32_e32 v92, 16, v78
	v_and_b32_e32 v93, 0xffff0000, v78
	v_mul_f32_e32 v78, 0xbfb8aa3b, v92
	v_exp_f32_e32 v78, v78
	v_and_b32_e32 v77, 0xffff0000, v86
	v_lshlrev_b32_e32 v76, 16, v86
	v_pk_mul_f32 v[76:77], v[88:89], v[76:77] op_sel_hi:[0,1]
	v_add_f32_e32 v78, 1.0, v78
	v_rcp_f32_e32 v94, v78
	v_mul_f32_e32 v78, 0xbfb8aa3b, v93
	v_exp_f32_e32 v78, v78
	v_lshlrev_b32_e32 v86, 16, v79
	v_add_f32_e32 v78, 1.0, v78
	v_rcp_f32_e32 v95, v78
	v_mul_f32_e32 v78, 0xbfb8aa3b, v86
	v_exp_f32_e32 v78, v78
	v_pk_mul_f32 v[92:93], v[94:95], v[92:93]
	s_nop 0
	v_pk_mul_f32 v[92:93], v[92:93], v[76:77]
	v_and_b32_e32 v77, 0xffff0000, v87
	v_lshlrev_b32_e32 v76, 16, v87
	v_and_b32_e32 v87, 0xffff0000, v79
	v_mul_f32_e32 v79, 0xbfb8aa3b, v87
	v_exp_f32_e32 v79, v79
	v_add_f32_e32 v78, 1.0, v78
	v_rcp_f32_e32 v78, v78
	v_pk_mul_f32 v[76:77], v[88:89], v[76:77] op_sel_hi:[0,1]
	v_add_f32_e32 v79, 1.0, v79
	v_rcp_f32_e32 v79, v79
	s_nop 0
	v_pk_mul_f32 v[78:79], v[78:79], v[86:87]
	s_nop 0
	v_pk_mul_f32 v[86:87], v[78:79], v[76:77]
	v_cvt_pk_bf16_f32 v76, v90, v91
	v_cvt_pk_bf16_f32 v79, v86, v87
	s_waitcnt vmcnt(0)
	v_lshlrev_b32_e32 v86, 16, v72
	v_and_b32_e32 v87, 0xffff0000, v72
	v_mul_f32_e32 v72, 0xbfb8aa3b, v86
	v_exp_f32_e32 v72, v72
	v_cvt_pk_bf16_f32 v77, v84, v85
	s_waitcnt lgkmcnt(0)
	v_and_b32_e32 v85, 0xffff0000, v80
	v_lshlrev_b32_e32 v84, 16, v80
	v_add_f32_e32 v72, 1.0, v72
	v_rcp_f32_e32 v90, v72
	v_mul_f32_e32 v72, 0xbfb8aa3b, v87
	v_exp_f32_e32 v72, v72
	v_pk_mul_f32 v[84:85], v[88:89], v[84:85] op_sel_hi:[0,1]
	v_lshlrev_b32_e32 v80, 16, v73
	v_cvt_pk_bf16_f32 v78, v92, v93
	v_add_f32_e32 v72, 1.0, v72
	v_rcp_f32_e32 v91, v72
	v_mul_f32_e32 v72, 0xbfb8aa3b, v80
	v_exp_f32_e32 v72, v72
	v_pk_mul_f32 v[86:87], v[90:91], v[86:87]
	s_nop 0
	v_pk_mul_f32 v[84:85], v[86:87], v[84:85]
	v_and_b32_e32 v87, 0xffff0000, v81
	v_lshlrev_b32_e32 v86, 16, v81
	v_and_b32_e32 v81, 0xffff0000, v73
	v_mul_f32_e32 v73, 0xbfb8aa3b, v81
	v_exp_f32_e32 v73, v73
	v_add_f32_e32 v72, 1.0, v72
	v_rcp_f32_e32 v72, v72
	v_pk_mul_f32 v[86:87], v[88:89], v[86:87] op_sel_hi:[0,1]
	v_add_f32_e32 v73, 1.0, v73
	v_rcp_f32_e32 v73, v73
	s_nop 0
	v_pk_mul_f32 v[72:73], v[72:73], v[80:81]
	s_nop 0
	v_pk_mul_f32 v[80:81], v[72:73], v[86:87]
	v_lshlrev_b32_e32 v86, 16, v74
	v_and_b32_e32 v87, 0xffff0000, v74
	v_mul_f32_e32 v74, 0xbfb8aa3b, v86
	v_exp_f32_e32 v74, v74
	v_and_b32_e32 v73, 0xffff0000, v82
	v_lshlrev_b32_e32 v72, 16, v82
	v_pk_mul_f32 v[72:73], v[88:89], v[72:73] op_sel_hi:[0,1]
	v_add_f32_e32 v74, 1.0, v74
	v_rcp_f32_e32 v90, v74
	v_mul_f32_e32 v74, 0xbfb8aa3b, v87
	v_exp_f32_e32 v74, v74
	v_lshlrev_b32_e32 v82, 16, v75
	v_add_f32_e32 v74, 1.0, v74
	v_rcp_f32_e32 v91, v74
	v_mul_f32_e32 v74, 0xbfb8aa3b, v82
	v_exp_f32_e32 v74, v74
	v_pk_mul_f32 v[86:87], v[90:91], v[86:87]
	s_nop 0
	v_pk_mul_f32 v[86:87], v[86:87], v[72:73]
	v_and_b32_e32 v73, 0xffff0000, v83
	v_lshlrev_b32_e32 v72, 16, v83
	v_and_b32_e32 v83, 0xffff0000, v75
	v_mul_f32_e32 v75, 0xbfb8aa3b, v83
	v_exp_f32_e32 v75, v75
	v_add_f32_e32 v74, 1.0, v74
	v_rcp_f32_e32 v74, v74
	v_pk_mul_f32 v[72:73], v[88:89], v[72:73] op_sel_hi:[0,1]
	v_add_f32_e32 v75, 1.0, v75
	v_rcp_f32_e32 v75, v75
	s_nop 0
	v_pk_mul_f32 v[74:75], v[74:75], v[82:83]
	s_nop 0
	v_pk_mul_f32 v[82:83], v[74:75], v[72:73]
	v_cvt_pk_bf16_f32 v73, v80, v81
	v_lshl_add_u64 v[80:81], s[92:93], 0, v[120:121]
	v_add_co_u32_e32 v80, vcc, s8, v80
	s_mov_b64 s[8:9], 0x20000
	v_lshl_add_u64 v[120:121], v[120:121], 0, s[8:9]
	s_mov_b64 s[8:9], 0x4000
	v_addc_co_u32_e32 v81, vcc, 0, v81, vcc
	v_lshl_add_u64 v[124:125], v[124:125], 0, s[8:9]
	v_cvt_pk_bf16_f32 v72, v84, v85
	v_cvt_pk_bf16_f32 v74, v86, v87
	v_cvt_pk_bf16_f32 v75, v82, v83
	global_store_dwordx4 v[80:81], v[76:79], off offset:1024
	global_store_dwordx4 v[80:81], v[72:75], off offset:1040
	s_barrier
	s_cbranch_scc0 .LBB0_706
